# saddr SP2+skip K loops in P1,P7,P13,P14 + P12 balance + pk zeroing
# baseline (speedup 1.0000x reference)
.LBB0_190:
	ds_read_b128 v[130:133], v155
	ds_read_b128 v[134:137], v155 offset:1024
	ds_read_b128 v[148:151], v155 offset:2048
	ds_read_b128 v[158:161], v155 offset:3072
	ds_read_b128 v[194:197], v157
	ds_read_b128 v[198:201], v157 offset:1024
	ds_read_b128 v[202:205], v157 offset:2048
	ds_read_b128 v[206:209], v157 offset:3072
	s_add_u32 s0, s64, 0xfffc0080
	s_addc_u32 s1, s65, -1
	s_cmp_eq_u32 s68, 12
	s_cselect_b32 s1, s11, s1
	s_cselect_b32 s0, s10, s0
	s_cselect_b32 s31, s63, s67
	s_cselect_b32 s30, s62, s66
	ds_read_b128 v[162:165], v156
	ds_read_b128 v[166:169], v156 offset:1024
	ds_read_b128 v[170:173], v156 offset:2048
	ds_read_b128 v[174:177], v156 offset:3072
	ds_read_b128 v[178:181], v156 offset:4096
	ds_read_b128 v[182:185], v156 offset:5120
	ds_read_b128 v[186:189], v156 offset:6144
	ds_read_b128 v[190:193], v156 offset:7168
	s_add_i32 m0, s7, 0xc000
	s_nop 0
	global_load_lds_dwordx4 v142, s[64:65]
	s_add_u32 s100, s64, s14
	s_addc_u32 s101, s65, s15
	s_add_i32 m0, s7, 0xe000
	s_nop 0
	global_load_lds_dwordx4 v142, s[100:101]
	s_cmp_lg_u32 s98, 0
	s_cbranch_scc1 .Lsk1_p1
	s_waitcnt vmcnt(8)
.Lsk1_p1:
	s_waitcnt lgkmcnt(0)
	s_barrier
	s_setprio 1
	v_mfma_f32_16x16x32_bf16 v[126:129], v[130:133], v[162:165], v[126:129]
	v_mfma_f32_16x16x32_bf16 v[122:125], v[148:151], v[162:165], v[122:125]
	v_mfma_f32_16x16x32_bf16 v[118:121], v[130:133], v[170:173], v[118:121]
	v_mfma_f32_16x16x32_bf16 v[114:117], v[148:151], v[170:173], v[114:117]
	v_mfma_f32_16x16x32_bf16 v[110:113], v[130:133], v[178:181], v[110:113]
	v_mfma_f32_16x16x32_bf16 v[106:109], v[148:151], v[178:181], v[106:109]
	v_mfma_f32_16x16x32_bf16 v[102:105], v[130:133], v[186:189], v[102:105]
	v_mfma_f32_16x16x32_bf16 v[98:101], v[148:151], v[186:189], v[98:101]
	v_mfma_f32_16x16x32_bf16 v[126:129], v[134:137], v[166:169], v[126:129]
	v_mfma_f32_16x16x32_bf16 v[122:125], v[158:161], v[166:169], v[122:125]
	v_mfma_f32_16x16x32_bf16 v[118:121], v[134:137], v[174:177], v[118:121]
	v_mfma_f32_16x16x32_bf16 v[114:117], v[158:161], v[174:177], v[114:117]
	v_mfma_f32_16x16x32_bf16 v[110:113], v[134:137], v[182:185], v[110:113]
	v_mfma_f32_16x16x32_bf16 v[106:109], v[158:161], v[182:185], v[106:109]
	v_mfma_f32_16x16x32_bf16 v[102:105], v[134:137], v[190:193], v[102:105]
	v_mfma_f32_16x16x32_bf16 v[98:101], v[158:161], v[190:193], v[98:101]
	v_mfma_f32_16x16x32_bf16 v[62:65], v[194:197], v[162:165], v[62:65]
	v_mfma_f32_16x16x32_bf16 v[58:61], v[202:205], v[162:165], v[58:61]
	v_mfma_f32_16x16x32_bf16 v[54:57], v[194:197], v[170:173], v[54:57]
	v_mfma_f32_16x16x32_bf16 v[50:53], v[202:205], v[170:173], v[50:53]
	v_mfma_f32_16x16x32_bf16 v[46:49], v[194:197], v[178:181], v[46:49]
	v_mfma_f32_16x16x32_bf16 v[42:45], v[202:205], v[178:181], v[42:45]
	v_mfma_f32_16x16x32_bf16 v[38:41], v[194:197], v[186:189], v[38:41]
	v_mfma_f32_16x16x32_bf16 v[34:37], v[202:205], v[186:189], v[34:37]
	v_mfma_f32_16x16x32_bf16 v[62:65], v[198:201], v[166:169], v[62:65]
	v_mfma_f32_16x16x32_bf16 v[58:61], v[206:209], v[166:169], v[58:61]
	v_mfma_f32_16x16x32_bf16 v[54:57], v[198:201], v[174:177], v[54:57]
	v_mfma_f32_16x16x32_bf16 v[50:53], v[206:209], v[174:177], v[50:53]
	v_mfma_f32_16x16x32_bf16 v[46:49], v[198:201], v[182:185], v[46:49]
	v_mfma_f32_16x16x32_bf16 v[42:45], v[206:209], v[182:185], v[42:45]
	v_mfma_f32_16x16x32_bf16 v[38:41], v[198:201], v[190:193], v[38:41]
	v_mfma_f32_16x16x32_bf16 v[34:37], v[206:209], v[190:193], v[34:37]
	s_setprio 0
	s_barrier
	ds_read_b128 v[162:165], v156 offset:16384
	ds_read_b128 v[166:169], v156 offset:17408
	ds_read_b128 v[170:173], v156 offset:18432
	ds_read_b128 v[174:177], v156 offset:19456
	ds_read_b128 v[178:181], v156 offset:20480
	ds_read_b128 v[182:185], v156 offset:21504
	ds_read_b128 v[186:189], v156 offset:22528
	ds_read_b128 v[190:193], v156 offset:23552
	s_add_i32 s99, s75, s5
	s_mov_b32 m0, s99
	s_nop 0
	global_load_lds_dwordx4 v138, s[30:31]
	s_add_u32 s100, s30, s14
	s_addc_u32 s101, s31, s15
	s_add_i32 m0, s99, 0x2000
	s_nop 0
	global_load_lds_dwordx4 v138, s[100:101]
	s_add_i32 s99, s76, s5
	s_add_u32 s100, s30, s16
	s_addc_u32 s101, s31, s17
	s_mov_b32 m0, s99
	s_nop 0
	global_load_lds_dwordx4 v138, s[100:101]
	s_add_u32 s100, s30, s18
	s_addc_u32 s101, s31, s19
	s_add_i32 m0, s99, 0x2000
	s_nop 0
	global_load_lds_dwordx4 v138, s[100:101]
	s_mov_b32 m0, s7
	s_nop 0
	global_load_lds_dwordx4 v140, s[0:1]
	s_add_u32 s100, s0, s14
	s_addc_u32 s101, s1, s15
	s_mov_b32 m0, s24
	s_nop 0
	global_load_lds_dwordx4 v140, s[100:101]
	s_cmp_lg_u32 s98, 0
	s_cbranch_scc1 .Lsk2_p1
	s_waitcnt vmcnt(8)
.Lsk2_p1:
	s_mov_b32 s98, 0
	s_waitcnt lgkmcnt(0)
	s_barrier
	s_setprio 1
	v_mfma_f32_16x16x32_bf16 v[94:97], v[130:133], v[162:165], v[94:97]
	v_mfma_f32_16x16x32_bf16 v[90:93], v[148:151], v[162:165], v[90:93]
	v_mfma_f32_16x16x32_bf16 v[86:89], v[130:133], v[170:173], v[86:89]
	v_mfma_f32_16x16x32_bf16 v[82:85], v[148:151], v[170:173], v[82:85]
	v_mfma_f32_16x16x32_bf16 v[78:81], v[130:133], v[178:181], v[78:81]
	v_mfma_f32_16x16x32_bf16 v[74:77], v[148:151], v[178:181], v[74:77]
	v_mfma_f32_16x16x32_bf16 v[70:73], v[130:133], v[186:189], v[70:73]
	v_mfma_f32_16x16x32_bf16 v[66:69], v[148:151], v[186:189], v[66:69]
	v_mfma_f32_16x16x32_bf16 v[94:97], v[134:137], v[166:169], v[94:97]
	v_mfma_f32_16x16x32_bf16 v[90:93], v[158:161], v[166:169], v[90:93]
	v_mfma_f32_16x16x32_bf16 v[86:89], v[134:137], v[174:177], v[86:89]
	v_mfma_f32_16x16x32_bf16 v[82:85], v[158:161], v[174:177], v[82:85]
	v_mfma_f32_16x16x32_bf16 v[78:81], v[134:137], v[182:185], v[78:81]
	v_mfma_f32_16x16x32_bf16 v[74:77], v[158:161], v[182:185], v[74:77]
	v_mfma_f32_16x16x32_bf16 v[70:73], v[134:137], v[190:193], v[70:73]
	v_mfma_f32_16x16x32_bf16 v[66:69], v[158:161], v[190:193], v[66:69]
	v_mfma_f32_16x16x32_bf16 v[30:33], v[194:197], v[162:165], v[30:33]
	v_mfma_f32_16x16x32_bf16 v[26:29], v[202:205], v[162:165], v[26:29]
	v_mfma_f32_16x16x32_bf16 v[22:25], v[194:197], v[170:173], v[22:25]
	v_mfma_f32_16x16x32_bf16 v[18:21], v[202:205], v[170:173], v[18:21]
	v_mfma_f32_16x16x32_bf16 v[14:17], v[194:197], v[178:181], v[14:17]
	v_mfma_f32_16x16x32_bf16 v[10:13], v[202:205], v[178:181], v[10:13]
	v_mfma_f32_16x16x32_bf16 v[6:9], v[194:197], v[186:189], v[6:9]
	v_mfma_f32_16x16x32_bf16 v[2:5], v[202:205], v[186:189], v[2:5]
	v_mfma_f32_16x16x32_bf16 v[30:33], v[198:201], v[166:169], v[30:33]
	v_mfma_f32_16x16x32_bf16 v[26:29], v[206:209], v[166:169], v[26:29]
	v_mfma_f32_16x16x32_bf16 v[22:25], v[198:201], v[174:177], v[22:25]
	v_mfma_f32_16x16x32_bf16 v[18:21], v[206:209], v[174:177], v[18:21]
	v_mfma_f32_16x16x32_bf16 v[14:17], v[198:201], v[182:185], v[14:17]
	v_mfma_f32_16x16x32_bf16 v[10:13], v[206:209], v[182:185], v[10:13]
	v_mfma_f32_16x16x32_bf16 v[6:9], v[198:201], v[190:193], v[6:9]
	v_mfma_f32_16x16x32_bf16 v[2:5], v[206:209], v[190:193], v[2:5]
	s_setprio 0
	v_add_u32_e32 v158, 0x18000, v154
	s_barrier
	v_add_u32_e32 v206, 0x1c000, v154
	ds_read_b128 v[130:133], v158
	ds_read_b128 v[134:137], v158 offset:1024
	ds_read_b128 v[148:151], v158 offset:2048
	ds_read_b128 v[158:161], v158 offset:3072
	ds_read_b128 v[194:197], v206
	ds_read_b128 v[198:201], v206 offset:1024
	ds_read_b128 v[202:205], v206 offset:2048
	ds_read_b128 v[206:209], v206 offset:3072
	ds_read_b128 v[162:165], v156 offset:32768
	ds_read_b128 v[166:169], v156 offset:33792
	ds_read_b128 v[170:173], v156 offset:34816
	ds_read_b128 v[174:177], v156 offset:35840
	ds_read_b128 v[178:181], v156 offset:36864
	ds_read_b128 v[182:185], v156 offset:37888
	ds_read_b128 v[186:189], v156 offset:38912
	ds_read_b128 v[190:193], v156 offset:39936
	s_add_u32 s100, s0, s16
	s_addc_u32 s101, s1, s17
	s_mov_b32 m0, s25
	s_nop 0
	global_load_lds_dwordx4 v140, s[100:101]
	s_add_u32 s100, s0, s18
	s_addc_u32 s101, s1, s19
	s_mov_b32 m0, s26
	s_nop 0
	global_load_lds_dwordx4 v140, s[100:101]
	s_waitcnt vmcnt(8)
	s_waitcnt lgkmcnt(0)
	s_barrier
	s_setprio 1
	v_mfma_f32_16x16x32_bf16 v[126:129], v[130:133], v[162:165], v[126:129]
	v_mfma_f32_16x16x32_bf16 v[122:125], v[148:151], v[162:165], v[122:125]
	v_mfma_f32_16x16x32_bf16 v[118:121], v[130:133], v[170:173], v[118:121]
	v_mfma_f32_16x16x32_bf16 v[114:117], v[148:151], v[170:173], v[114:117]
	v_mfma_f32_16x16x32_bf16 v[110:113], v[130:133], v[178:181], v[110:113]
	v_mfma_f32_16x16x32_bf16 v[106:109], v[148:151], v[178:181], v[106:109]
	v_mfma_f32_16x16x32_bf16 v[102:105], v[130:133], v[186:189], v[102:105]
	v_mfma_f32_16x16x32_bf16 v[98:101], v[148:151], v[186:189], v[98:101]
	v_mfma_f32_16x16x32_bf16 v[126:129], v[134:137], v[166:169], v[126:129]
	v_mfma_f32_16x16x32_bf16 v[122:125], v[158:161], v[166:169], v[122:125]
	v_mfma_f32_16x16x32_bf16 v[118:121], v[134:137], v[174:177], v[118:121]
	v_mfma_f32_16x16x32_bf16 v[114:117], v[158:161], v[174:177], v[114:117]
	v_mfma_f32_16x16x32_bf16 v[110:113], v[134:137], v[182:185], v[110:113]
	v_mfma_f32_16x16x32_bf16 v[106:109], v[158:161], v[182:185], v[106:109]
	v_mfma_f32_16x16x32_bf16 v[102:105], v[134:137], v[190:193], v[102:105]
	v_mfma_f32_16x16x32_bf16 v[98:101], v[158:161], v[190:193], v[98:101]
	v_mfma_f32_16x16x32_bf16 v[62:65], v[194:197], v[162:165], v[62:65]
	v_mfma_f32_16x16x32_bf16 v[58:61], v[202:205], v[162:165], v[58:61]
	v_mfma_f32_16x16x32_bf16 v[54:57], v[194:197], v[170:173], v[54:57]
	v_mfma_f32_16x16x32_bf16 v[50:53], v[202:205], v[170:173], v[50:53]
	v_mfma_f32_16x16x32_bf16 v[46:49], v[194:197], v[178:181], v[46:49]
	v_mfma_f32_16x16x32_bf16 v[42:45], v[202:205], v[178:181], v[42:45]
	v_mfma_f32_16x16x32_bf16 v[38:41], v[194:197], v[186:189], v[38:41]
	v_mfma_f32_16x16x32_bf16 v[34:37], v[202:205], v[186:189], v[34:37]
	v_mfma_f32_16x16x32_bf16 v[62:65], v[198:201], v[166:169], v[62:65]
	v_mfma_f32_16x16x32_bf16 v[58:61], v[206:209], v[166:169], v[58:61]
	v_mfma_f32_16x16x32_bf16 v[54:57], v[198:201], v[174:177], v[54:57]
	v_mfma_f32_16x16x32_bf16 v[50:53], v[206:209], v[174:177], v[50:53]
	v_mfma_f32_16x16x32_bf16 v[46:49], v[198:201], v[182:185], v[46:49]
	v_mfma_f32_16x16x32_bf16 v[42:45], v[206:209], v[182:185], v[42:45]
	v_mfma_f32_16x16x32_bf16 v[38:41], v[198:201], v[190:193], v[38:41]
	v_mfma_f32_16x16x32_bf16 v[34:37], v[206:209], v[190:193], v[34:37]
	s_setprio 0
	s_barrier
	ds_read_b128 v[162:165], v156 offset:49152
	ds_read_b128 v[166:169], v156 offset:50176
	ds_read_b128 v[170:173], v156 offset:51200
	ds_read_b128 v[174:177], v156 offset:52224
	ds_read_b128 v[178:181], v156 offset:53248
	ds_read_b128 v[182:185], v156 offset:54272
	ds_read_b128 v[186:189], v156 offset:55296
	ds_read_b128 v[190:193], v156 offset:56320
	s_add_i32 s99, s5, 0x18000
	s_add_u32 s100, s30, s38
	s_addc_u32 s101, s31, s39
	s_mov_b32 m0, s99
	s_nop 0
	global_load_lds_dwordx4 v138, s[100:101]
	s_add_u32 s100, s30, s42
	s_addc_u32 s101, s31, s43
	s_add_i32 m0, s99, 0x2000
	s_nop 0
	global_load_lds_dwordx4 v138, s[100:101]
	s_add_i32 s99, s5, 0x1c000
	s_add_u32 s100, s30, s44
	s_addc_u32 s101, s31, s45
	s_mov_b32 m0, s99
	s_nop 0
	global_load_lds_dwordx4 v138, s[100:101]
	s_add_u32 s100, s30, s46
	s_addc_u32 s101, s31, s47
	s_add_i32 m0, s99, 0x2000
	s_nop 0
	global_load_lds_dwordx4 v138, s[100:101]
	s_add_u32 s100, s0, s38
	s_addc_u32 s101, s1, s39
	s_mov_b32 m0, s37
	s_nop 0
	global_load_lds_dwordx4 v140, s[100:101]
	s_add_u32 s100, s0, s42
	s_addc_u32 s101, s1, s43
	s_mov_b32 m0, s40
	s_nop 0
	global_load_lds_dwordx4 v140, s[100:101]
	s_waitcnt vmcnt(8)
	s_waitcnt lgkmcnt(0)
	s_barrier
	s_setprio 1
	v_mfma_f32_16x16x32_bf16 v[94:97], v[130:133], v[162:165], v[94:97]
	v_mfma_f32_16x16x32_bf16 v[90:93], v[148:151], v[162:165], v[90:93]
	v_mfma_f32_16x16x32_bf16 v[86:89], v[130:133], v[170:173], v[86:89]
	v_mfma_f32_16x16x32_bf16 v[82:85], v[148:151], v[170:173], v[82:85]
	v_mfma_f32_16x16x32_bf16 v[78:81], v[130:133], v[178:181], v[78:81]
	v_mfma_f32_16x16x32_bf16 v[74:77], v[148:151], v[178:181], v[74:77]
	v_mfma_f32_16x16x32_bf16 v[70:73], v[130:133], v[186:189], v[70:73]
	v_mfma_f32_16x16x32_bf16 v[66:69], v[148:151], v[186:189], v[66:69]
	v_mfma_f32_16x16x32_bf16 v[94:97], v[134:137], v[166:169], v[94:97]
	v_mfma_f32_16x16x32_bf16 v[90:93], v[158:161], v[166:169], v[90:93]
	v_mfma_f32_16x16x32_bf16 v[86:89], v[134:137], v[174:177], v[86:89]
	v_mfma_f32_16x16x32_bf16 v[82:85], v[158:161], v[174:177], v[82:85]
	v_mfma_f32_16x16x32_bf16 v[78:81], v[134:137], v[182:185], v[78:81]
	v_mfma_f32_16x16x32_bf16 v[74:77], v[158:161], v[182:185], v[74:77]
	v_mfma_f32_16x16x32_bf16 v[70:73], v[134:137], v[190:193], v[70:73]
	v_mfma_f32_16x16x32_bf16 v[66:69], v[158:161], v[190:193], v[66:69]
	v_mfma_f32_16x16x32_bf16 v[30:33], v[194:197], v[162:165], v[30:33]
	v_mfma_f32_16x16x32_bf16 v[26:29], v[202:205], v[162:165], v[26:29]
	v_mfma_f32_16x16x32_bf16 v[22:25], v[194:197], v[170:173], v[22:25]
	v_mfma_f32_16x16x32_bf16 v[18:21], v[202:205], v[170:173], v[18:21]
	v_mfma_f32_16x16x32_bf16 v[14:17], v[194:197], v[178:181], v[14:17]
	v_mfma_f32_16x16x32_bf16 v[10:13], v[202:205], v[178:181], v[10:13]
	v_mfma_f32_16x16x32_bf16 v[6:9], v[194:197], v[186:189], v[6:9]
	v_mfma_f32_16x16x32_bf16 v[2:5], v[202:205], v[186:189], v[2:5]
	v_mfma_f32_16x16x32_bf16 v[30:33], v[198:201], v[166:169], v[30:33]
	v_mfma_f32_16x16x32_bf16 v[26:29], v[206:209], v[166:169], v[26:29]
	v_mfma_f32_16x16x32_bf16 v[22:25], v[198:201], v[174:177], v[22:25]
	v_mfma_f32_16x16x32_bf16 v[18:21], v[206:209], v[174:177], v[18:21]
	v_mfma_f32_16x16x32_bf16 v[14:17], v[198:201], v[182:185], v[14:17]
	v_mfma_f32_16x16x32_bf16 v[10:13], v[206:209], v[182:185], v[10:13]
	v_mfma_f32_16x16x32_bf16 v[6:9], v[198:201], v[190:193], v[6:9]
	v_mfma_f32_16x16x32_bf16 v[2:5], v[206:209], v[190:193], v[2:5]
	s_setprio 0
	s_add_i32 s68, s68, 2
	s_add_u32 s66, s66, 0x100
	s_addc_u32 s67, s67, 0
	s_add_u32 s64, s64, 0x100
	s_addc_u32 s65, s65, 0
	s_cmp_gt_u32 s68, 13
	s_barrier
	s_cbranch_scc0 .LBB0_190
	s_mov_b32 s98, 1
	s_and_b64 vcc, exec, s[48:49]
	s_cbranch_vccz .LBB0_193
	s_barrier

.LBB0_1049:
	ds_read_b128 v[130:133], v155
	ds_read_b128 v[134:137], v155 offset:1024
	ds_read_b128 v[148:151], v155 offset:2048
	ds_read_b128 v[158:161], v155 offset:3072
	ds_read_b128 v[194:197], v157
	ds_read_b128 v[198:201], v157 offset:1024
	ds_read_b128 v[202:205], v157 offset:2048
	ds_read_b128 v[206:209], v157 offset:3072
	s_add_u32 s0, s66, 0xfffc0080
	s_addc_u32 s1, s67, -1
	s_cmp_eq_u32 s69, 12
	s_cselect_b32 s1, s13, s1
	s_cselect_b32 s0, s12, s0
	s_cselect_b32 s31, s65, s68
	s_cselect_b32 s30, s64, s38
	ds_read_b128 v[162:165], v156
	ds_read_b128 v[166:169], v156 offset:1024
	ds_read_b128 v[170:173], v156 offset:2048
	ds_read_b128 v[174:177], v156 offset:3072
	ds_read_b128 v[178:181], v156 offset:4096
	ds_read_b128 v[182:185], v156 offset:5120
	ds_read_b128 v[186:189], v156 offset:6144
	ds_read_b128 v[190:193], v156 offset:7168
	s_add_i32 m0, s9, 0xc000
	s_nop 0
	global_load_lds_dwordx4 v142, s[66:67]
	s_add_u32 s100, s66, s14
	s_addc_u32 s101, s67, s15
	s_add_i32 m0, s9, 0xe000
	s_nop 0
	global_load_lds_dwordx4 v142, s[100:101]
	s_cmp_lg_u32 s98, 0
	s_cbranch_scc1 .Lsk1_p7
	s_waitcnt vmcnt(8)
.Lsk1_p7:
	s_waitcnt lgkmcnt(0)
	s_barrier
	s_setprio 1
	v_mfma_f32_16x16x32_bf16 v[126:129], v[130:133], v[162:165], v[126:129]
	v_mfma_f32_16x16x32_bf16 v[122:125], v[148:151], v[162:165], v[122:125]
	v_mfma_f32_16x16x32_bf16 v[118:121], v[130:133], v[170:173], v[118:121]
	v_mfma_f32_16x16x32_bf16 v[114:117], v[148:151], v[170:173], v[114:117]
	v_mfma_f32_16x16x32_bf16 v[110:113], v[130:133], v[178:181], v[110:113]
	v_mfma_f32_16x16x32_bf16 v[106:109], v[148:151], v[178:181], v[106:109]
	v_mfma_f32_16x16x32_bf16 v[102:105], v[130:133], v[186:189], v[102:105]
	v_mfma_f32_16x16x32_bf16 v[98:101], v[148:151], v[186:189], v[98:101]
	v_mfma_f32_16x16x32_bf16 v[126:129], v[134:137], v[166:169], v[126:129]
	v_mfma_f32_16x16x32_bf16 v[122:125], v[158:161], v[166:169], v[122:125]
	v_mfma_f32_16x16x32_bf16 v[118:121], v[134:137], v[174:177], v[118:121]
	v_mfma_f32_16x16x32_bf16 v[114:117], v[158:161], v[174:177], v[114:117]
	v_mfma_f32_16x16x32_bf16 v[110:113], v[134:137], v[182:185], v[110:113]
	v_mfma_f32_16x16x32_bf16 v[106:109], v[158:161], v[182:185], v[106:109]
	v_mfma_f32_16x16x32_bf16 v[102:105], v[134:137], v[190:193], v[102:105]
	v_mfma_f32_16x16x32_bf16 v[98:101], v[158:161], v[190:193], v[98:101]
	v_mfma_f32_16x16x32_bf16 v[62:65], v[194:197], v[162:165], v[62:65]
	v_mfma_f32_16x16x32_bf16 v[58:61], v[202:205], v[162:165], v[58:61]
	v_mfma_f32_16x16x32_bf16 v[54:57], v[194:197], v[170:173], v[54:57]
	v_mfma_f32_16x16x32_bf16 v[50:53], v[202:205], v[170:173], v[50:53]
	v_mfma_f32_16x16x32_bf16 v[46:49], v[194:197], v[178:181], v[46:49]
	v_mfma_f32_16x16x32_bf16 v[42:45], v[202:205], v[178:181], v[42:45]
	v_mfma_f32_16x16x32_bf16 v[38:41], v[194:197], v[186:189], v[38:41]
	v_mfma_f32_16x16x32_bf16 v[34:37], v[202:205], v[186:189], v[34:37]
	v_mfma_f32_16x16x32_bf16 v[62:65], v[198:201], v[166:169], v[62:65]
	v_mfma_f32_16x16x32_bf16 v[58:61], v[206:209], v[166:169], v[58:61]
	v_mfma_f32_16x16x32_bf16 v[54:57], v[198:201], v[174:177], v[54:57]
	v_mfma_f32_16x16x32_bf16 v[50:53], v[206:209], v[174:177], v[50:53]
	v_mfma_f32_16x16x32_bf16 v[46:49], v[198:201], v[182:185], v[46:49]
	v_mfma_f32_16x16x32_bf16 v[42:45], v[206:209], v[182:185], v[42:45]
	v_mfma_f32_16x16x32_bf16 v[38:41], v[198:201], v[190:193], v[38:41]
	v_mfma_f32_16x16x32_bf16 v[34:37], v[206:209], v[190:193], v[34:37]
	s_setprio 0
	s_barrier
	ds_read_b128 v[162:165], v156 offset:16384
	ds_read_b128 v[166:169], v156 offset:17408
	ds_read_b128 v[170:173], v156 offset:18432
	ds_read_b128 v[174:177], v156 offset:19456
	ds_read_b128 v[178:181], v156 offset:20480
	ds_read_b128 v[182:185], v156 offset:21504
	ds_read_b128 v[186:189], v156 offset:22528
	ds_read_b128 v[190:193], v156 offset:23552
	s_add_i32 s99, s78, s7
	s_mov_b32 m0, s99
	s_nop 0
	global_load_lds_dwordx4 v138, s[30:31]
	s_add_u32 s100, s30, s14
	s_addc_u32 s101, s31, s15
	s_add_i32 m0, s99, 0x2000
	s_nop 0
	global_load_lds_dwordx4 v138, s[100:101]
	s_add_i32 s99, s79, s7
	s_add_u32 s100, s30, s18
	s_addc_u32 s101, s31, s19
	s_mov_b32 m0, s99
	s_nop 0
	global_load_lds_dwordx4 v138, s[100:101]
	s_add_u32 s100, s30, s20
	s_addc_u32 s101, s31, s21
	s_add_i32 m0, s99, 0x2000
	s_nop 0
	global_load_lds_dwordx4 v138, s[100:101]
	s_mov_b32 m0, s9
	s_nop 0
	global_load_lds_dwordx4 v140, s[0:1]
	s_add_u32 s100, s0, s14
	s_addc_u32 s101, s1, s15
	s_mov_b32 m0, s24
	s_nop 0
	global_load_lds_dwordx4 v140, s[100:101]
	s_cmp_lg_u32 s98, 0
	s_cbranch_scc1 .Lsk2_p7
	s_waitcnt vmcnt(8)
.Lsk2_p7:
	s_mov_b32 s98, 0
	s_waitcnt lgkmcnt(0)
	s_barrier
	s_setprio 1
	v_mfma_f32_16x16x32_bf16 v[94:97], v[130:133], v[162:165], v[94:97]
	v_mfma_f32_16x16x32_bf16 v[90:93], v[148:151], v[162:165], v[90:93]
	v_mfma_f32_16x16x32_bf16 v[86:89], v[130:133], v[170:173], v[86:89]
	v_mfma_f32_16x16x32_bf16 v[82:85], v[148:151], v[170:173], v[82:85]
	v_mfma_f32_16x16x32_bf16 v[78:81], v[130:133], v[178:181], v[78:81]
	v_mfma_f32_16x16x32_bf16 v[74:77], v[148:151], v[178:181], v[74:77]
	v_mfma_f32_16x16x32_bf16 v[70:73], v[130:133], v[186:189], v[70:73]
	v_mfma_f32_16x16x32_bf16 v[66:69], v[148:151], v[186:189], v[66:69]
	v_mfma_f32_16x16x32_bf16 v[94:97], v[134:137], v[166:169], v[94:97]
	v_mfma_f32_16x16x32_bf16 v[90:93], v[158:161], v[166:169], v[90:93]
	v_mfma_f32_16x16x32_bf16 v[86:89], v[134:137], v[174:177], v[86:89]
	v_mfma_f32_16x16x32_bf16 v[82:85], v[158:161], v[174:177], v[82:85]
	v_mfma_f32_16x16x32_bf16 v[78:81], v[134:137], v[182:185], v[78:81]
	v_mfma_f32_16x16x32_bf16 v[74:77], v[158:161], v[182:185], v[74:77]
	v_mfma_f32_16x16x32_bf16 v[70:73], v[134:137], v[190:193], v[70:73]
	v_mfma_f32_16x16x32_bf16 v[66:69], v[158:161], v[190:193], v[66:69]
	v_mfma_f32_16x16x32_bf16 v[30:33], v[194:197], v[162:165], v[30:33]
	v_mfma_f32_16x16x32_bf16 v[26:29], v[202:205], v[162:165], v[26:29]
	v_mfma_f32_16x16x32_bf16 v[22:25], v[194:197], v[170:173], v[22:25]
	v_mfma_f32_16x16x32_bf16 v[18:21], v[202:205], v[170:173], v[18:21]
	v_mfma_f32_16x16x32_bf16 v[14:17], v[194:197], v[178:181], v[14:17]
	v_mfma_f32_16x16x32_bf16 v[10:13], v[202:205], v[178:181], v[10:13]
	v_mfma_f32_16x16x32_bf16 v[6:9], v[194:197], v[186:189], v[6:9]
	v_mfma_f32_16x16x32_bf16 v[2:5], v[202:205], v[186:189], v[2:5]
	v_mfma_f32_16x16x32_bf16 v[30:33], v[198:201], v[166:169], v[30:33]
	v_mfma_f32_16x16x32_bf16 v[26:29], v[206:209], v[166:169], v[26:29]
	v_mfma_f32_16x16x32_bf16 v[22:25], v[198:201], v[174:177], v[22:25]
	v_mfma_f32_16x16x32_bf16 v[18:21], v[206:209], v[174:177], v[18:21]
	v_mfma_f32_16x16x32_bf16 v[14:17], v[198:201], v[182:185], v[14:17]
	v_mfma_f32_16x16x32_bf16 v[10:13], v[206:209], v[182:185], v[10:13]
	v_mfma_f32_16x16x32_bf16 v[6:9], v[198:201], v[190:193], v[6:9]
	v_mfma_f32_16x16x32_bf16 v[2:5], v[206:209], v[190:193], v[2:5]
	s_setprio 0
	v_add_u32_e32 v158, 0x18000, v154
	s_barrier
	v_add_u32_e32 v206, 0x1c000, v154
	ds_read_b128 v[130:133], v158
	ds_read_b128 v[134:137], v158 offset:1024
	ds_read_b128 v[148:151], v158 offset:2048
	ds_read_b128 v[158:161], v158 offset:3072
	ds_read_b128 v[194:197], v206
	ds_read_b128 v[198:201], v206 offset:1024
	ds_read_b128 v[202:205], v206 offset:2048
	ds_read_b128 v[206:209], v206 offset:3072
	ds_read_b128 v[162:165], v156 offset:32768
	ds_read_b128 v[166:169], v156 offset:33792
	ds_read_b128 v[170:173], v156 offset:34816
	ds_read_b128 v[174:177], v156 offset:35840
	ds_read_b128 v[178:181], v156 offset:36864
	ds_read_b128 v[182:185], v156 offset:37888
	ds_read_b128 v[186:189], v156 offset:38912
	ds_read_b128 v[190:193], v156 offset:39936
	s_add_u32 s100, s0, s18
	s_addc_u32 s101, s1, s19
	s_mov_b32 m0, s25
	s_nop 0
	global_load_lds_dwordx4 v140, s[100:101]
	s_add_u32 s100, s0, s20
	s_addc_u32 s101, s1, s21
	s_mov_b32 m0, s26
	s_nop 0
	global_load_lds_dwordx4 v140, s[100:101]
	s_waitcnt vmcnt(8)
	s_waitcnt lgkmcnt(0)
	s_barrier
	s_setprio 1
	v_mfma_f32_16x16x32_bf16 v[126:129], v[130:133], v[162:165], v[126:129]
	v_mfma_f32_16x16x32_bf16 v[122:125], v[148:151], v[162:165], v[122:125]
	v_mfma_f32_16x16x32_bf16 v[118:121], v[130:133], v[170:173], v[118:121]
	v_mfma_f32_16x16x32_bf16 v[114:117], v[148:151], v[170:173], v[114:117]
	v_mfma_f32_16x16x32_bf16 v[110:113], v[130:133], v[178:181], v[110:113]
	v_mfma_f32_16x16x32_bf16 v[106:109], v[148:151], v[178:181], v[106:109]
	v_mfma_f32_16x16x32_bf16 v[102:105], v[130:133], v[186:189], v[102:105]
	v_mfma_f32_16x16x32_bf16 v[98:101], v[148:151], v[186:189], v[98:101]
	v_mfma_f32_16x16x32_bf16 v[126:129], v[134:137], v[166:169], v[126:129]
	v_mfma_f32_16x16x32_bf16 v[122:125], v[158:161], v[166:169], v[122:125]
	v_mfma_f32_16x16x32_bf16 v[118:121], v[134:137], v[174:177], v[118:121]
	v_mfma_f32_16x16x32_bf16 v[114:117], v[158:161], v[174:177], v[114:117]
	v_mfma_f32_16x16x32_bf16 v[110:113], v[134:137], v[182:185], v[110:113]
	v_mfma_f32_16x16x32_bf16 v[106:109], v[158:161], v[182:185], v[106:109]
	v_mfma_f32_16x16x32_bf16 v[102:105], v[134:137], v[190:193], v[102:105]
	v_mfma_f32_16x16x32_bf16 v[98:101], v[158:161], v[190:193], v[98:101]
	v_mfma_f32_16x16x32_bf16 v[62:65], v[194:197], v[162:165], v[62:65]
	v_mfma_f32_16x16x32_bf16 v[58:61], v[202:205], v[162:165], v[58:61]
	v_mfma_f32_16x16x32_bf16 v[54:57], v[194:197], v[170:173], v[54:57]
	v_mfma_f32_16x16x32_bf16 v[50:53], v[202:205], v[170:173], v[50:53]
	v_mfma_f32_16x16x32_bf16 v[46:49], v[194:197], v[178:181], v[46:49]
	v_mfma_f32_16x16x32_bf16 v[42:45], v[202:205], v[178:181], v[42:45]
	v_mfma_f32_16x16x32_bf16 v[38:41], v[194:197], v[186:189], v[38:41]
	v_mfma_f32_16x16x32_bf16 v[34:37], v[202:205], v[186:189], v[34:37]
	v_mfma_f32_16x16x32_bf16 v[62:65], v[198:201], v[166:169], v[62:65]
	v_mfma_f32_16x16x32_bf16 v[58:61], v[206:209], v[166:169], v[58:61]
	v_mfma_f32_16x16x32_bf16 v[54:57], v[198:201], v[174:177], v[54:57]
	v_mfma_f32_16x16x32_bf16 v[50:53], v[206:209], v[174:177], v[50:53]
	v_mfma_f32_16x16x32_bf16 v[46:49], v[198:201], v[182:185], v[46:49]
	v_mfma_f32_16x16x32_bf16 v[42:45], v[206:209], v[182:185], v[42:45]
	v_mfma_f32_16x16x32_bf16 v[38:41], v[198:201], v[190:193], v[38:41]
	v_mfma_f32_16x16x32_bf16 v[34:37], v[206:209], v[190:193], v[34:37]
	s_setprio 0
	s_barrier
	ds_read_b128 v[162:165], v156 offset:49152
	ds_read_b128 v[166:169], v156 offset:50176
	ds_read_b128 v[170:173], v156 offset:51200
	ds_read_b128 v[174:177], v156 offset:52224
	ds_read_b128 v[178:181], v156 offset:53248
	ds_read_b128 v[182:185], v156 offset:54272
	ds_read_b128 v[186:189], v156 offset:55296
	ds_read_b128 v[190:193], v156 offset:56320
	s_add_i32 s99, s7, 0x18000
	s_add_u32 s100, s30, s42
	s_addc_u32 s101, s31, s43
	s_mov_b32 m0, s99
	s_nop 0
	global_load_lds_dwordx4 v138, s[100:101]
	s_add_u32 s100, s30, s44
	s_addc_u32 s101, s31, s45
	s_add_i32 m0, s99, 0x2000
	s_nop 0
	global_load_lds_dwordx4 v138, s[100:101]
	s_add_i32 s99, s7, 0x1c000
	s_add_u32 s100, s30, s46
	s_addc_u32 s101, s31, s47
	s_mov_b32 m0, s99
	s_nop 0
	global_load_lds_dwordx4 v138, s[100:101]
	s_add_u32 s100, s30, s48
	s_addc_u32 s101, s31, s49
	s_add_i32 m0, s99, 0x2000
	s_nop 0
	global_load_lds_dwordx4 v138, s[100:101]
	s_add_u32 s100, s0, s42
	s_addc_u32 s101, s1, s43
	s_mov_b32 m0, s72
	s_nop 0
	global_load_lds_dwordx4 v140, s[100:101]
	s_add_u32 s100, s0, s44
	s_addc_u32 s101, s1, s45
	s_mov_b32 m0, s73
	s_nop 0
	global_load_lds_dwordx4 v140, s[100:101]
	s_waitcnt vmcnt(8)
	s_waitcnt lgkmcnt(0)
	s_barrier
	s_setprio 1
	v_mfma_f32_16x16x32_bf16 v[94:97], v[130:133], v[162:165], v[94:97]
	v_mfma_f32_16x16x32_bf16 v[90:93], v[148:151], v[162:165], v[90:93]
	v_mfma_f32_16x16x32_bf16 v[86:89], v[130:133], v[170:173], v[86:89]
	v_mfma_f32_16x16x32_bf16 v[82:85], v[148:151], v[170:173], v[82:85]
	v_mfma_f32_16x16x32_bf16 v[78:81], v[130:133], v[178:181], v[78:81]
	v_mfma_f32_16x16x32_bf16 v[74:77], v[148:151], v[178:181], v[74:77]
	v_mfma_f32_16x16x32_bf16 v[70:73], v[130:133], v[186:189], v[70:73]
	v_mfma_f32_16x16x32_bf16 v[66:69], v[148:151], v[186:189], v[66:69]
	v_mfma_f32_16x16x32_bf16 v[94:97], v[134:137], v[166:169], v[94:97]
	v_mfma_f32_16x16x32_bf16 v[90:93], v[158:161], v[166:169], v[90:93]
	v_mfma_f32_16x16x32_bf16 v[86:89], v[134:137], v[174:177], v[86:89]
	v_mfma_f32_16x16x32_bf16 v[82:85], v[158:161], v[174:177], v[82:85]
	v_mfma_f32_16x16x32_bf16 v[78:81], v[134:137], v[182:185], v[78:81]
	v_mfma_f32_16x16x32_bf16 v[74:77], v[158:161], v[182:185], v[74:77]
	v_mfma_f32_16x16x32_bf16 v[70:73], v[134:137], v[190:193], v[70:73]
	v_mfma_f32_16x16x32_bf16 v[66:69], v[158:161], v[190:193], v[66:69]
	v_mfma_f32_16x16x32_bf16 v[30:33], v[194:197], v[162:165], v[30:33]
	v_mfma_f32_16x16x32_bf16 v[26:29], v[202:205], v[162:165], v[26:29]
	v_mfma_f32_16x16x32_bf16 v[22:25], v[194:197], v[170:173], v[22:25]
	v_mfma_f32_16x16x32_bf16 v[18:21], v[202:205], v[170:173], v[18:21]
	v_mfma_f32_16x16x32_bf16 v[14:17], v[194:197], v[178:181], v[14:17]
	v_mfma_f32_16x16x32_bf16 v[10:13], v[202:205], v[178:181], v[10:13]
	v_mfma_f32_16x16x32_bf16 v[6:9], v[194:197], v[186:189], v[6:9]
	v_mfma_f32_16x16x32_bf16 v[2:5], v[202:205], v[186:189], v[2:5]
	v_mfma_f32_16x16x32_bf16 v[30:33], v[198:201], v[166:169], v[30:33]
	v_mfma_f32_16x16x32_bf16 v[26:29], v[206:209], v[166:169], v[26:29]
	v_mfma_f32_16x16x32_bf16 v[22:25], v[198:201], v[174:177], v[22:25]
	v_mfma_f32_16x16x32_bf16 v[18:21], v[206:209], v[174:177], v[18:21]
	v_mfma_f32_16x16x32_bf16 v[14:17], v[198:201], v[182:185], v[14:17]
	v_mfma_f32_16x16x32_bf16 v[10:13], v[206:209], v[182:185], v[10:13]
	v_mfma_f32_16x16x32_bf16 v[6:9], v[198:201], v[190:193], v[6:9]
	v_mfma_f32_16x16x32_bf16 v[2:5], v[206:209], v[190:193], v[2:5]
	s_setprio 0
	s_add_i32 s69, s69, 2
	s_add_u32 s38, s38, 0x100
	s_addc_u32 s68, s68, 0
	s_add_u32 s66, s66, 0x100
	s_addc_u32 s67, s67, 0
	s_cmp_gt_u32 s69, 13
	s_barrier
	s_cbranch_scc0 .LBB0_1049
	s_mov_b32 s98, 1
	s_and_b64 vcc, exec, s[50:51]
	s_cbranch_vccz .LBB0_1052
	s_barrier

.LBB0_1631:
	ds_read_b128 v[122:125], v189
	ds_read_b128 v[134:137], v189 offset:1024
	ds_read_b128 v[138:141], v189 offset:2048
	ds_read_b128 v[142:145], v189 offset:3072
	ds_read_b128 v[192:195], v191
	ds_read_b128 v[196:199], v191 offset:1024
	ds_read_b128 v[200:203], v191 offset:2048
	ds_read_b128 v[204:207], v191 offset:3072
	s_add_u32 s0, s60, 0xfffc0080
	s_addc_u32 s1, s61, -1
	s_cmp_eq_u32 s79, 12
	s_cselect_b32 s1, s57, s1
	s_cselect_b32 s0, s56, s0
	s_cselect_b32 s31, s59, s63
	s_cselect_b32 s30, s58, s62
	ds_read_b128 v[146:149], v190
	ds_read_b128 v[150:153], v190 offset:1024
	ds_read_b128 v[154:157], v190 offset:2048
	ds_read_b128 v[158:161], v190 offset:3072
	ds_read_b128 v[168:171], v190 offset:4096
	ds_read_b128 v[172:175], v190 offset:5120
	ds_read_b128 v[176:179], v190 offset:6144
	ds_read_b128 v[180:183], v190 offset:7168
	s_add_i32 m0, s6, 0xc000
	s_nop 0
	global_load_lds_dwordx4 v166, s[60:61]
	s_add_u32 s100, s60, s12
	s_addc_u32 s101, s61, s13
	s_add_i32 m0, s6, 0xe000
	s_nop 0
	global_load_lds_dwordx4 v166, s[100:101]
	s_cmp_lg_u32 s98, 0
	s_cbranch_scc1 .Lsk1_p13
	s_waitcnt vmcnt(8)
.Lsk1_p13:
	s_waitcnt lgkmcnt(0)
	s_barrier
	s_setprio 1
	v_mfma_f32_16x16x32_bf16 v[130:133], v[122:125], v[146:149], v[130:133]
	v_mfma_f32_16x16x32_bf16 v[126:129], v[138:141], v[146:149], v[126:129]
	v_mfma_f32_16x16x32_bf16 v[118:121], v[122:125], v[154:157], v[118:121]
	v_mfma_f32_16x16x32_bf16 v[114:117], v[138:141], v[154:157], v[114:117]
	v_mfma_f32_16x16x32_bf16 v[110:113], v[122:125], v[168:171], v[110:113]
	v_mfma_f32_16x16x32_bf16 v[106:109], v[138:141], v[168:171], v[106:109]
	v_mfma_f32_16x16x32_bf16 v[102:105], v[122:125], v[176:179], v[102:105]
	v_mfma_f32_16x16x32_bf16 v[98:101], v[138:141], v[176:179], v[98:101]
	v_mfma_f32_16x16x32_bf16 v[130:133], v[134:137], v[150:153], v[130:133]
	v_mfma_f32_16x16x32_bf16 v[126:129], v[142:145], v[150:153], v[126:129]
	v_mfma_f32_16x16x32_bf16 v[118:121], v[134:137], v[158:161], v[118:121]
	v_mfma_f32_16x16x32_bf16 v[114:117], v[142:145], v[158:161], v[114:117]
	v_mfma_f32_16x16x32_bf16 v[110:113], v[134:137], v[172:175], v[110:113]
	v_mfma_f32_16x16x32_bf16 v[106:109], v[142:145], v[172:175], v[106:109]
	v_mfma_f32_16x16x32_bf16 v[102:105], v[134:137], v[180:183], v[102:105]
	v_mfma_f32_16x16x32_bf16 v[98:101], v[142:145], v[180:183], v[98:101]
	v_mfma_f32_16x16x32_bf16 v[62:65], v[192:195], v[146:149], v[62:65]
	v_mfma_f32_16x16x32_bf16 v[58:61], v[200:203], v[146:149], v[58:61]
	v_mfma_f32_16x16x32_bf16 v[54:57], v[192:195], v[154:157], v[54:57]
	v_mfma_f32_16x16x32_bf16 v[50:53], v[200:203], v[154:157], v[50:53]
	v_mfma_f32_16x16x32_bf16 v[46:49], v[192:195], v[168:171], v[46:49]
	v_mfma_f32_16x16x32_bf16 v[42:45], v[200:203], v[168:171], v[42:45]
	v_mfma_f32_16x16x32_bf16 v[38:41], v[192:195], v[176:179], v[38:41]
	v_mfma_f32_16x16x32_bf16 v[34:37], v[200:203], v[176:179], v[34:37]
	v_mfma_f32_16x16x32_bf16 v[62:65], v[196:199], v[150:153], v[62:65]
	v_mfma_f32_16x16x32_bf16 v[58:61], v[204:207], v[150:153], v[58:61]
	v_mfma_f32_16x16x32_bf16 v[54:57], v[196:199], v[158:161], v[54:57]
	v_mfma_f32_16x16x32_bf16 v[50:53], v[204:207], v[158:161], v[50:53]
	v_mfma_f32_16x16x32_bf16 v[46:49], v[196:199], v[172:175], v[46:49]
	v_mfma_f32_16x16x32_bf16 v[42:45], v[204:207], v[172:175], v[42:45]
	v_mfma_f32_16x16x32_bf16 v[38:41], v[196:199], v[180:183], v[38:41]
	v_mfma_f32_16x16x32_bf16 v[34:37], v[204:207], v[180:183], v[34:37]
	s_setprio 0
	s_barrier
	ds_read_b128 v[146:149], v190 offset:16384
	ds_read_b128 v[150:153], v190 offset:17408
	ds_read_b128 v[154:157], v190 offset:18432
	ds_read_b128 v[158:161], v190 offset:19456
	ds_read_b128 v[168:171], v190 offset:20480
	ds_read_b128 v[172:175], v190 offset:21504
	ds_read_b128 v[176:179], v190 offset:22528
	ds_read_b128 v[180:183], v190 offset:23552
	s_add_i32 s99, s72, s5
	s_mov_b32 m0, s99
	s_nop 0
	global_load_lds_dwordx4 v162, s[30:31]
	s_add_u32 s100, s30, s12
	s_addc_u32 s101, s31, s13
	s_add_i32 m0, s99, 0x2000
	s_nop 0
	global_load_lds_dwordx4 v162, s[100:101]
	s_add_i32 s99, s73, s5
	s_add_u32 s100, s30, s14
	s_addc_u32 s101, s31, s15
	s_mov_b32 m0, s99
	s_nop 0
	global_load_lds_dwordx4 v162, s[100:101]
	s_add_u32 s100, s30, s16
	s_addc_u32 s101, s31, s17
	s_add_i32 m0, s99, 0x2000
	s_nop 0
	global_load_lds_dwordx4 v162, s[100:101]
	s_mov_b32 m0, s6
	s_nop 0
	global_load_lds_dwordx4 v164, s[0:1]
	s_add_u32 s100, s0, s12
	s_addc_u32 s101, s1, s13
	s_mov_b32 m0, s7
	s_nop 0
	global_load_lds_dwordx4 v164, s[100:101]
	s_cmp_lg_u32 s98, 0
	s_cbranch_scc1 .Lsk2_p13
	s_waitcnt vmcnt(8)
.Lsk2_p13:
	s_mov_b32 s98, 0
	s_waitcnt lgkmcnt(0)
	s_barrier
	s_setprio 1
	v_mfma_f32_16x16x32_bf16 v[94:97], v[122:125], v[146:149], v[94:97]
	v_mfma_f32_16x16x32_bf16 v[90:93], v[138:141], v[146:149], v[90:93]
	v_mfma_f32_16x16x32_bf16 v[86:89], v[122:125], v[154:157], v[86:89]
	v_mfma_f32_16x16x32_bf16 v[82:85], v[138:141], v[154:157], v[82:85]
	v_mfma_f32_16x16x32_bf16 v[78:81], v[122:125], v[168:171], v[78:81]
	v_mfma_f32_16x16x32_bf16 v[74:77], v[138:141], v[168:171], v[74:77]
	v_mfma_f32_16x16x32_bf16 v[70:73], v[122:125], v[176:179], v[70:73]
	v_mfma_f32_16x16x32_bf16 v[66:69], v[138:141], v[176:179], v[66:69]
	v_mfma_f32_16x16x32_bf16 v[94:97], v[134:137], v[150:153], v[94:97]
	v_mfma_f32_16x16x32_bf16 v[90:93], v[142:145], v[150:153], v[90:93]
	v_mfma_f32_16x16x32_bf16 v[86:89], v[134:137], v[158:161], v[86:89]
	v_mfma_f32_16x16x32_bf16 v[82:85], v[142:145], v[158:161], v[82:85]
	v_mfma_f32_16x16x32_bf16 v[78:81], v[134:137], v[172:175], v[78:81]
	v_mfma_f32_16x16x32_bf16 v[74:77], v[142:145], v[172:175], v[74:77]
	v_mfma_f32_16x16x32_bf16 v[70:73], v[134:137], v[180:183], v[70:73]
	v_mfma_f32_16x16x32_bf16 v[66:69], v[142:145], v[180:183], v[66:69]
	v_mfma_f32_16x16x32_bf16 v[30:33], v[192:195], v[146:149], v[30:33]
	v_mfma_f32_16x16x32_bf16 v[26:29], v[200:203], v[146:149], v[26:29]
	v_mfma_f32_16x16x32_bf16 v[22:25], v[192:195], v[154:157], v[22:25]
	v_mfma_f32_16x16x32_bf16 v[18:21], v[200:203], v[154:157], v[18:21]
	v_mfma_f32_16x16x32_bf16 v[14:17], v[192:195], v[168:171], v[14:17]
	v_mfma_f32_16x16x32_bf16 v[10:13], v[200:203], v[168:171], v[10:13]
	v_mfma_f32_16x16x32_bf16 v[6:9], v[192:195], v[176:179], v[6:9]
	v_mfma_f32_16x16x32_bf16 v[2:5], v[200:203], v[176:179], v[2:5]
	v_mfma_f32_16x16x32_bf16 v[30:33], v[196:199], v[150:153], v[30:33]
	v_mfma_f32_16x16x32_bf16 v[26:29], v[204:207], v[150:153], v[26:29]
	v_mfma_f32_16x16x32_bf16 v[22:25], v[196:199], v[158:161], v[22:25]
	v_mfma_f32_16x16x32_bf16 v[18:21], v[204:207], v[158:161], v[18:21]
	v_mfma_f32_16x16x32_bf16 v[14:17], v[196:199], v[172:175], v[14:17]
	v_mfma_f32_16x16x32_bf16 v[10:13], v[204:207], v[172:175], v[10:13]
	v_mfma_f32_16x16x32_bf16 v[6:9], v[196:199], v[180:183], v[6:9]
	v_mfma_f32_16x16x32_bf16 v[2:5], v[204:207], v[180:183], v[2:5]
	s_setprio 0
	v_add_u32_e32 v142, 0x18000, v188
	s_barrier
	v_add_u32_e32 v204, 0x1c000, v188
	ds_read_b128 v[122:125], v142
	ds_read_b128 v[134:137], v142 offset:1024
	ds_read_b128 v[138:141], v142 offset:2048
	ds_read_b128 v[142:145], v142 offset:3072
	ds_read_b128 v[192:195], v204
	ds_read_b128 v[196:199], v204 offset:1024
	ds_read_b128 v[200:203], v204 offset:2048
	ds_read_b128 v[204:207], v204 offset:3072
	ds_read_b128 v[146:149], v190 offset:32768
	ds_read_b128 v[150:153], v190 offset:33792
	ds_read_b128 v[154:157], v190 offset:34816
	ds_read_b128 v[158:161], v190 offset:35840
	ds_read_b128 v[168:171], v190 offset:36864
	ds_read_b128 v[172:175], v190 offset:37888
	ds_read_b128 v[176:179], v190 offset:38912
	ds_read_b128 v[180:183], v190 offset:39936
	s_add_u32 s100, s0, s14
	s_addc_u32 s101, s1, s15
	s_mov_b32 m0, s24
	s_nop 0
	global_load_lds_dwordx4 v164, s[100:101]
	s_add_u32 s100, s0, s16
	s_addc_u32 s101, s1, s17
	s_mov_b32 m0, s25
	s_nop 0
	global_load_lds_dwordx4 v164, s[100:101]
	s_waitcnt vmcnt(8)
	s_waitcnt lgkmcnt(0)
	s_barrier
	s_setprio 1
	v_mfma_f32_16x16x32_bf16 v[130:133], v[122:125], v[146:149], v[130:133]
	v_mfma_f32_16x16x32_bf16 v[126:129], v[138:141], v[146:149], v[126:129]
	v_mfma_f32_16x16x32_bf16 v[118:121], v[122:125], v[154:157], v[118:121]
	v_mfma_f32_16x16x32_bf16 v[114:117], v[138:141], v[154:157], v[114:117]
	v_mfma_f32_16x16x32_bf16 v[110:113], v[122:125], v[168:171], v[110:113]
	v_mfma_f32_16x16x32_bf16 v[106:109], v[138:141], v[168:171], v[106:109]
	v_mfma_f32_16x16x32_bf16 v[102:105], v[122:125], v[176:179], v[102:105]
	v_mfma_f32_16x16x32_bf16 v[98:101], v[138:141], v[176:179], v[98:101]
	v_mfma_f32_16x16x32_bf16 v[130:133], v[134:137], v[150:153], v[130:133]
	v_mfma_f32_16x16x32_bf16 v[126:129], v[142:145], v[150:153], v[126:129]
	v_mfma_f32_16x16x32_bf16 v[118:121], v[134:137], v[158:161], v[118:121]
	v_mfma_f32_16x16x32_bf16 v[114:117], v[142:145], v[158:161], v[114:117]
	v_mfma_f32_16x16x32_bf16 v[110:113], v[134:137], v[172:175], v[110:113]
	v_mfma_f32_16x16x32_bf16 v[106:109], v[142:145], v[172:175], v[106:109]
	v_mfma_f32_16x16x32_bf16 v[102:105], v[134:137], v[180:183], v[102:105]
	v_mfma_f32_16x16x32_bf16 v[98:101], v[142:145], v[180:183], v[98:101]
	v_mfma_f32_16x16x32_bf16 v[62:65], v[192:195], v[146:149], v[62:65]
	v_mfma_f32_16x16x32_bf16 v[58:61], v[200:203], v[146:149], v[58:61]
	v_mfma_f32_16x16x32_bf16 v[54:57], v[192:195], v[154:157], v[54:57]
	v_mfma_f32_16x16x32_bf16 v[50:53], v[200:203], v[154:157], v[50:53]
	v_mfma_f32_16x16x32_bf16 v[46:49], v[192:195], v[168:171], v[46:49]
	v_mfma_f32_16x16x32_bf16 v[42:45], v[200:203], v[168:171], v[42:45]
	v_mfma_f32_16x16x32_bf16 v[38:41], v[192:195], v[176:179], v[38:41]
	v_mfma_f32_16x16x32_bf16 v[34:37], v[200:203], v[176:179], v[34:37]
	v_mfma_f32_16x16x32_bf16 v[62:65], v[196:199], v[150:153], v[62:65]
	v_mfma_f32_16x16x32_bf16 v[58:61], v[204:207], v[150:153], v[58:61]
	v_mfma_f32_16x16x32_bf16 v[54:57], v[196:199], v[158:161], v[54:57]
	v_mfma_f32_16x16x32_bf16 v[50:53], v[204:207], v[158:161], v[50:53]
	v_mfma_f32_16x16x32_bf16 v[46:49], v[196:199], v[172:175], v[46:49]
	v_mfma_f32_16x16x32_bf16 v[42:45], v[204:207], v[172:175], v[42:45]
	v_mfma_f32_16x16x32_bf16 v[38:41], v[196:199], v[180:183], v[38:41]
	v_mfma_f32_16x16x32_bf16 v[34:37], v[204:207], v[180:183], v[34:37]
	s_setprio 0
	s_barrier
	ds_read_b128 v[146:149], v190 offset:49152
	ds_read_b128 v[150:153], v190 offset:50176
	ds_read_b128 v[154:157], v190 offset:51200
	ds_read_b128 v[158:161], v190 offset:52224
	ds_read_b128 v[168:171], v190 offset:53248
	ds_read_b128 v[172:175], v190 offset:54272
	ds_read_b128 v[176:179], v190 offset:55296
	ds_read_b128 v[180:183], v190 offset:56320
	s_add_i32 s99, s5, 0x18000
	s_add_u32 s100, s30, s22
	s_addc_u32 s101, s31, s23
	s_mov_b32 m0, s99
	s_nop 0
	global_load_lds_dwordx4 v162, s[100:101]
	s_add_u32 s100, s30, s34
	s_addc_u32 s101, s31, s35
	s_add_i32 m0, s99, 0x2000
	s_nop 0
	global_load_lds_dwordx4 v162, s[100:101]
	s_add_i32 s99, s5, 0x1c000
	s_add_u32 s100, s30, s36
	s_addc_u32 s101, s31, s37
	s_mov_b32 m0, s99
	s_nop 0
	global_load_lds_dwordx4 v162, s[100:101]
	s_add_u32 s100, s30, s38
	s_addc_u32 s101, s31, s39
	s_add_i32 m0, s99, 0x2000
	s_nop 0
	global_load_lds_dwordx4 v162, s[100:101]
	s_add_u32 s100, s0, s22
	s_addc_u32 s101, s1, s23
	s_mov_b32 m0, s66
	s_nop 0
	global_load_lds_dwordx4 v164, s[100:101]
	s_add_u32 s100, s0, s34
	s_addc_u32 s101, s1, s35
	s_mov_b32 m0, s67
	s_nop 0
	global_load_lds_dwordx4 v164, s[100:101]
	s_waitcnt vmcnt(8)
	s_waitcnt lgkmcnt(0)
	s_barrier
	s_setprio 1
	v_mfma_f32_16x16x32_bf16 v[94:97], v[122:125], v[146:149], v[94:97]
	v_mfma_f32_16x16x32_bf16 v[90:93], v[138:141], v[146:149], v[90:93]
	v_mfma_f32_16x16x32_bf16 v[86:89], v[122:125], v[154:157], v[86:89]
	v_mfma_f32_16x16x32_bf16 v[82:85], v[138:141], v[154:157], v[82:85]
	v_mfma_f32_16x16x32_bf16 v[78:81], v[122:125], v[168:171], v[78:81]
	v_mfma_f32_16x16x32_bf16 v[74:77], v[138:141], v[168:171], v[74:77]
	v_mfma_f32_16x16x32_bf16 v[70:73], v[122:125], v[176:179], v[70:73]
	v_mfma_f32_16x16x32_bf16 v[66:69], v[138:141], v[176:179], v[66:69]
	v_mfma_f32_16x16x32_bf16 v[94:97], v[134:137], v[150:153], v[94:97]
	v_mfma_f32_16x16x32_bf16 v[90:93], v[142:145], v[150:153], v[90:93]
	v_mfma_f32_16x16x32_bf16 v[86:89], v[134:137], v[158:161], v[86:89]
	v_mfma_f32_16x16x32_bf16 v[82:85], v[142:145], v[158:161], v[82:85]
	v_mfma_f32_16x16x32_bf16 v[78:81], v[134:137], v[172:175], v[78:81]
	v_mfma_f32_16x16x32_bf16 v[74:77], v[142:145], v[172:175], v[74:77]
	v_mfma_f32_16x16x32_bf16 v[70:73], v[134:137], v[180:183], v[70:73]
	v_mfma_f32_16x16x32_bf16 v[66:69], v[142:145], v[180:183], v[66:69]
	v_mfma_f32_16x16x32_bf16 v[30:33], v[192:195], v[146:149], v[30:33]
	v_mfma_f32_16x16x32_bf16 v[26:29], v[200:203], v[146:149], v[26:29]
	v_mfma_f32_16x16x32_bf16 v[22:25], v[192:195], v[154:157], v[22:25]
	v_mfma_f32_16x16x32_bf16 v[18:21], v[200:203], v[154:157], v[18:21]
	v_mfma_f32_16x16x32_bf16 v[14:17], v[192:195], v[168:171], v[14:17]
	v_mfma_f32_16x16x32_bf16 v[10:13], v[200:203], v[168:171], v[10:13]
	v_mfma_f32_16x16x32_bf16 v[6:9], v[192:195], v[176:179], v[6:9]
	v_mfma_f32_16x16x32_bf16 v[2:5], v[200:203], v[176:179], v[2:5]
	v_mfma_f32_16x16x32_bf16 v[30:33], v[196:199], v[150:153], v[30:33]
	v_mfma_f32_16x16x32_bf16 v[26:29], v[204:207], v[150:153], v[26:29]
	v_mfma_f32_16x16x32_bf16 v[22:25], v[196:199], v[158:161], v[22:25]
	v_mfma_f32_16x16x32_bf16 v[18:21], v[204:207], v[158:161], v[18:21]
	v_mfma_f32_16x16x32_bf16 v[14:17], v[196:199], v[172:175], v[14:17]
	v_mfma_f32_16x16x32_bf16 v[10:13], v[204:207], v[172:175], v[10:13]
	v_mfma_f32_16x16x32_bf16 v[6:9], v[196:199], v[180:183], v[6:9]
	v_mfma_f32_16x16x32_bf16 v[2:5], v[204:207], v[180:183], v[2:5]
	s_setprio 0
	s_add_i32 s79, s79, 2
	s_add_u32 s62, s62, 0x100
	s_addc_u32 s63, s63, 0
	s_add_u32 s60, s60, 0x100
	s_addc_u32 s61, s61, 0
	s_cmp_gt_u32 s79, 13
	s_barrier
	s_cbranch_scc0 .LBB0_1631
	s_mov_b32 s98, 1
	s_and_b64 vcc, exec, s[40:41]
	s_cbranch_vccz .LBB0_1634
	s_barrier
